# MLA tile staging: quarter-rate 32-bit and 64-bit integer multiplies replaced by 24-bit forms (identical results)
# speedup vs baseline: 1.0176x; 1.0000x over previous
; #define LAS __attribute__((address_space(3)))
;     __device__ __forceinline__ void load(int t) {
;         unsigned tid = this->tid; asm volatile("" : "+v"(tid));
;         const char* knt = kn + (size_t)t * (64 * 2048); const char* krt = kr + (size_t)t * (64 * 128); const char* vtt = vt + (size_t)t * 128;
; #pragma unroll
;         for (int i = 0; i < 2; ++i) { const unsigned c = tid + 512u * i; rk[i] = *(const u32x4*)(knt + ((c >> 4) * 2048u + (c & 15u) * 16u)); }
;         rk[2] = *(const u32x4*)(krt + ((tid >> 3) * 128u + (tid & 7u) * 16u));
; #pragma unroll
;         for (int i = 0; i < 2; ++i) { const unsigned c = tid + 512u * i; rv[i] = *(const u32x4*)(vtt + ((c >> 3) * (unsigned)(VT_LD * 2) + (c & 7u) * 16u)); }
;         if ((t + 1) * 64 > nkeys) {
; #pragma unroll
;             for (int i = 0; i < 2; ++i) { const unsigned c = tid + 512u * i; if (t * 64 + (int)(c & 7u) * 8 >= nkeys) rv[i] = (u32x4){0u, 0u, 0u, 0u}; } }
;     }
;     __device__ __forceinline__ void store(LAS unsigned char* kb, LAS unsigned char* vb) const {
;         unsigned tid = this->tid; asm volatile("" : "+v"(tid));
; #pragma unroll
;         for (int i = 0; i < 2; ++i) { const unsigned c = tid + 512u * i; *(LAS u32x4*)(kb + (c >> 4) * 400u + (c & 15u) * 16u) = rk[i]; }
;         *(LAS u32x4*)(kb + (tid >> 3) * 400u + 256u + (tid & 7u) * 16u) = rk[2];
; #pragma unroll
;         for (int i = 0; i < 2; ++i) { const unsigned c = tid + 512u * i; LAS unsigned char* d = vb + (c >> 3) * (unsigned)AT_VSTR + (c & 7u) * 16u;
;             *(LAS u32x2*)d = (u32x2){rv[i].x, rv[i].y}; *(LAS u32x2*)(d + 8) = (u32x2){rv[i].z, rv[i].w}; }
;     }
.LBB0_4930:
	s_and_b32 s88, s87, 1
	s_xor_b32 s89, s88, 1
	v_mov_b32_e32 v33, v184
	s_mul_i32 s90, s89, 0x6400
	s_add_i32 s92, s90, 0
	v_lshlrev_b32_e32 v38, 4, v33
	v_and_b32_e32 v34, 0xf0, v38
	v_add_u32_e32 v34, s92, v34
	v_lshrrev_b32_e32 v35, 4, v33
	v_mad_u32_u24 v36, v35, s64, v34
	s_waitcnt vmcnt(4)
	ds_write_b128 v36, v[160:163]
	v_add_u32_e32 v36, 0x200, v33
	v_lshrrev_b32_e32 v35, 4, v36
	v_mad_u32_u24 v34, v35, s64, v34
	v_lshrrev_b32_e32 v33, 3, v33
	s_lshl_b32 s89, s89, 13
	s_waitcnt vmcnt(2)
	ds_write_b128 v34, v[164:167]
	v_mul_u32_u24_e64 v34, v33, s64
	v_and_b32_e32 v35, 0x70, v38
	s_sub_i32 s89, s92, s89
	v_add3_u32 v34, s92, v34, v35
	ds_write_b128 v34, v[168:171] offset:256
	v_add_u32_e32 v34, s89, v35
	v_mul_u32_u24_e64 v33, v33, s33
	v_add3_u32 v33, v34, v33, s2
	s_waitcnt vmcnt(1)
	ds_write2_b64 v33, v[172:173], v[174:175] offset1:1
	v_lshrrev_b32_e32 v33, 3, v36
	v_mul_u32_u24_e64 v33, v33, s33
	s_add_i32 s89, s87, 2
	v_add3_u32 v33, v34, v33, s2
	s_cmp_ge_u32 s89, s26
	s_waitcnt vmcnt(0)
	ds_write2_b64 v33, v[176:177], v[178:179] offset1:1
	s_cbranch_scc1 .LBB0_4933
	v_mov_b32_e32 v33, v184
	s_add_u32 s90, s4, s18
	v_lshlrev_b32_e32 v35, 4, v33
	v_lshlrev_b32_e32 v34, 7, v33
	v_and_b32_e32 v36, 0xf0, v35
	v_and_or_b32 v34, v34, s3, v36
	s_addc_u32 s91, s5, s19
	global_load_dwordx4 v[160:163], v34, s[90:91]
	v_add_u32_e32 v34, 0x10000, v34
	global_load_dwordx4 v[164:167], v34, s[90:91]
	s_add_u32 s90, s4, s60
	s_addc_u32 s91, s5, s61
	v_and_b32_e32 v34, 0x70, v35
	global_load_dwordx4 v[168:171], v35, s[90:91]
	v_lshrrev_b32_e32 v35, 3, v33
	v_add_u32_e32 v33, 0x200, v33
	v_lshrrev_b32_e32 v33, 3, v33
	v_mul_u32_u24_e64 v35, v35, s21
	s_add_u32 s90, s4, s62
	v_mul_u32_u24_e64 v33, v33, s21
	v_or_b32_e32 v35, v35, v34
	s_addc_u32 s91, s5, s63
	v_or_b32_e32 v33, v33, v34
	global_load_dwordx4 v[172:175], v35, s[90:91]
	global_load_dwordx4 v[176:179], v33, s[90:91]
	s_cmpk_lt_u32 s87, 0x7e
	s_cbranch_scc1 .LBB0_4933
	v_mov_b32_e32 v34, v32
	v_mov_b32_e32 v35, v32
	v_mov_b32_e32 v33, v32
	s_waitcnt vmcnt(0)
	v_mov_b64_e32 v[178:179], v[34:35]
	v_mov_b64_e32 v[174:175], v[34:35]
	v_mov_b64_e32 v[176:177], v[32:33]
	v_mov_b64_e32 v[172:173], v[32:33]
